# k_mean phase: the 256 serialised 2-byte loads per item (a full wait after each) issued 32 at a time off one address, same accumulation order
# speedup vs baseline: 1.0037x; 1.0013x over previous
; #define TIDX get_tid_()
; DI size_t kfrag_idx(int pos, int d) { return ((size_t)((pos >> 5) * 4 + (d >> 4)) * 64 + ((d >> 3) & 1) * 32 + (pos & 31)) * 8 + (d & 7); }
; DI bf16_t f2bf(float x) { unsigned r; asm("v_cvt_pk_bf16_f32 %0, %1, %1" : "=v"(r) : "v"(x)); return (bf16_t)(r & 0xffffu); }
; DI float bf2f(bf16_t b) { return __uint_as_float(((unsigned)b) << 16); }
; DI void kmean_phase(const Params& p) {
;   const int lane = TIDX & 63;
;   const int gw = blockIdx.x * 8 + (TIDX >> 6), nw = gridDim.x * 8;
;   const bf16_t* KM = (const bf16_t*)(p.ws + OFF_KM);
;   bf16_t* o = (bf16_t*)(p.ws + OFF_KMEAN);
;   for (int it = gw; it < 512; it += nw) {
;     const bf16_t* src = KM + (size_t)it * 256 * 64;
;     float s = 0.f;
;     for (int k = 0; k < 256; ++k) s += bf2f(KM[(size_t)(it >> 4) * 262144 + kfrag_idx((it & 15) * 256 + k, lane)]);
;     o[it * 64 + lane] = f2bf(s * (1.f / 256.f));
;   }
; }
.LBB0_1000:
	v_or_b32_e32 v9, s14, v7
	v_lshrrev_b32_e32 v9, 3, v9
	s_movk_i32 s15, 0x1fc
	v_and_or_b32 v9, v9, s15, v4
	v_lshlrev_b32_e32 v9, 6, v9
	s_and_b32 s15, s14, 24
	v_or3_b32 v9, v9, s15, v5
	v_lshl_or_b32 v130, v9, 3, v6
	v_lshl_add_u64 v[10:11], v[130:131], 1, v[0:1]
	global_load_ushort v12, v[10:11], off
	global_load_ushort v13, v[10:11], off offset:16
	global_load_ushort v14, v[10:11], off offset:32
	global_load_ushort v15, v[10:11], off offset:48
	global_load_ushort v16, v[10:11], off offset:64
	global_load_ushort v17, v[10:11], off offset:80
	global_load_ushort v18, v[10:11], off offset:96
	global_load_ushort v19, v[10:11], off offset:112
	global_load_ushort v20, v[10:11], off offset:128
	global_load_ushort v21, v[10:11], off offset:144
	global_load_ushort v22, v[10:11], off offset:160
	global_load_ushort v23, v[10:11], off offset:176
	global_load_ushort v24, v[10:11], off offset:192
	global_load_ushort v25, v[10:11], off offset:208
	global_load_ushort v26, v[10:11], off offset:224
	global_load_ushort v27, v[10:11], off offset:240
	global_load_ushort v28, v[10:11], off offset:256
	global_load_ushort v29, v[10:11], off offset:272
	global_load_ushort v30, v[10:11], off offset:288
	global_load_ushort v31, v[10:11], off offset:304
	global_load_ushort v32, v[10:11], off offset:320
	global_load_ushort v33, v[10:11], off offset:336
	global_load_ushort v34, v[10:11], off offset:352
	global_load_ushort v35, v[10:11], off offset:368
	global_load_ushort v36, v[10:11], off offset:384
	global_load_ushort v37, v[10:11], off offset:400
	global_load_ushort v38, v[10:11], off offset:416
	global_load_ushort v39, v[10:11], off offset:432
	global_load_ushort v40, v[10:11], off offset:448
	global_load_ushort v41, v[10:11], off offset:464
	global_load_ushort v42, v[10:11], off offset:480
	global_load_ushort v43, v[10:11], off offset:496
	s_add_i32 s14, s14, 32
	s_cmpk_eq_i32 s14, 0x100
	s_waitcnt vmcnt(0)
	v_lshlrev_b32_e32 v12, 16, v12
	v_add_f32_e32 v8, v8, v12
	v_lshlrev_b32_e32 v13, 16, v13
	v_add_f32_e32 v8, v8, v13
	v_lshlrev_b32_e32 v14, 16, v14
	v_add_f32_e32 v8, v8, v14
	v_lshlrev_b32_e32 v15, 16, v15
	v_add_f32_e32 v8, v8, v15
	v_lshlrev_b32_e32 v16, 16, v16
	v_add_f32_e32 v8, v8, v16
	v_lshlrev_b32_e32 v17, 16, v17
	v_add_f32_e32 v8, v8, v17
	v_lshlrev_b32_e32 v18, 16, v18
	v_add_f32_e32 v8, v8, v18
	v_lshlrev_b32_e32 v19, 16, v19
	v_add_f32_e32 v8, v8, v19
	v_lshlrev_b32_e32 v20, 16, v20
	v_add_f32_e32 v8, v8, v20
	v_lshlrev_b32_e32 v21, 16, v21
	v_add_f32_e32 v8, v8, v21
	v_lshlrev_b32_e32 v22, 16, v22
	v_add_f32_e32 v8, v8, v22
	v_lshlrev_b32_e32 v23, 16, v23
	v_add_f32_e32 v8, v8, v23
	v_lshlrev_b32_e32 v24, 16, v24
	v_add_f32_e32 v8, v8, v24
	v_lshlrev_b32_e32 v25, 16, v25
	v_add_f32_e32 v8, v8, v25
	v_lshlrev_b32_e32 v26, 16, v26
	v_add_f32_e32 v8, v8, v26
	v_lshlrev_b32_e32 v27, 16, v27
	v_add_f32_e32 v8, v8, v27
	v_lshlrev_b32_e32 v28, 16, v28
	v_add_f32_e32 v8, v8, v28
	v_lshlrev_b32_e32 v29, 16, v29
	v_add_f32_e32 v8, v8, v29
	v_lshlrev_b32_e32 v30, 16, v30
	v_add_f32_e32 v8, v8, v30
	v_lshlrev_b32_e32 v31, 16, v31
	v_add_f32_e32 v8, v8, v31
	v_lshlrev_b32_e32 v32, 16, v32
	v_add_f32_e32 v8, v8, v32
	v_lshlrev_b32_e32 v33, 16, v33
	v_add_f32_e32 v8, v8, v33
	v_lshlrev_b32_e32 v34, 16, v34
	v_add_f32_e32 v8, v8, v34
	v_lshlrev_b32_e32 v35, 16, v35
	v_add_f32_e32 v8, v8, v35
	v_lshlrev_b32_e32 v36, 16, v36
	v_add_f32_e32 v8, v8, v36
	v_lshlrev_b32_e32 v37, 16, v37
	v_add_f32_e32 v8, v8, v37
	v_lshlrev_b32_e32 v38, 16, v38
	v_add_f32_e32 v8, v8, v38
	v_lshlrev_b32_e32 v39, 16, v39
	v_add_f32_e32 v8, v8, v39
	v_lshlrev_b32_e32 v40, 16, v40
	v_add_f32_e32 v8, v8, v40
	v_lshlrev_b32_e32 v41, 16, v41
	v_add_f32_e32 v8, v8, v41
	v_lshlrev_b32_e32 v42, 16, v42
	v_add_f32_e32 v8, v8, v42
	v_lshlrev_b32_e32 v43, 16, v43
	v_add_f32_e32 v8, v8, v43
	s_cbranch_scc0 .LBB0_1000
	v_mul_f32_e32 v0, 0x3b800000, v8
	v_cvt_pk_bf16_f32 v7, v0, v0
	v_lshl_or_b32 v0, v2, 6, v3
	v_readlane_b32 s14, v253, 47
	v_ashrrev_i32_e32 v1, 31, v0
	v_readlane_b32 s15, v253, 48
	s_nop 1
	v_lshl_add_u64 v[0:1], v[0:1], 1, s[14:15]
	v_readlane_b32 s14, v252, 0
	v_readlane_b32 s15, v252, 1
	global_store_short v[0:1], v7, off
	v_add_u32_e32 v2, s14, v2
	s_movk_i32 s14, 0x1ff
	v_cmp_lt_i32_e32 vcc, s14, v2
	s_or_b64 s[10:11], vcc, s[10:11]
	s_andn2_b64 exec, exec, s[10:11]
	s_cbranch_execnz .LBB0_999
